# grid barriers: all waiters poll the top-level arrival counter (count >= (episode+1)*nXCD) instead of the generation word bumped by the last leader after its arrival returned
# baseline (speedup 1.0000x reference)
; __device__ __forceinline__ unsigned xb_ld(unsigned* p)              { return __hip_atomic_load(p, __ATOMIC_RELAXED, __HIP_MEMORY_SCOPE_AGENT); }
; __device__ __forceinline__ unsigned xb_add(unsigned* p, unsigned v) { return __hip_atomic_fetch_add(p, v, __ATOMIC_RELAXED, __HIP_MEMORY_SCOPE_AGENT); }
; #define XB_SPIN(cond, bar) do { unsigned _sp = 0; while (cond) { __builtin_amdgcn_s_sleep(1); \
;     if ((++_sp & 255u) == 0u) { if (xb_ld(&(bar)[XB_TMO])) break; if (_sp > XB_SPIN_CAP) { atomicAdd(&(bar)[XB_TMO], 1u); break; } } } } while (0)
; __device__ __forceinline__ void xcd_barrier(const XcdBarrier& b) {
;     ...
;         const unsigned old = xb_add(&bar[XB_XSUB(b.x)], 1u);
;         const unsigned gen = old / nloc;
;         if (old + 1u == (gen + 1u) * nloc) {
;             __builtin_amdgcn_fence(__ATOMIC_RELEASE, "agent");
;             asm volatile("s_waitcnt vmcnt(0)" ::: "memory");
;             const unsigned og = xb_add(&bar[XB_TOP], 1u);
;             const unsigned tg = og / nx;
;             if (og + 1u == (tg + 1u) * nx) xb_add(&bar[XB_TOPGEN], 1u);
;             else XB_SPIN(xb_ld(&bar[XB_TOPGEN]) == tg, bar);
;             __builtin_amdgcn_fence(__ATOMIC_ACQUIRE, "agent");
;             xb_add(&bar[XB_XGEN(b.x)], 1u);
;             asm volatile("s_waitcnt vmcnt(0)" ::: "memory");
;         } else {
;             XB_SPIN(xb_ld(&bar[XB_XGEN(b.x)]) == gen, bar);
;             __builtin_amdgcn_fence(__ATOMIC_ACQUIRE, "agent");
;             asm volatile("s_waitcnt vmcnt(0)" ::: "memory");
.LBB0_88:
	s_or_b64 exec, exec, s[8:9]
	v_cvt_f32_u32_e32 v4, v2
	s_waitcnt vmcnt(0)
	v_readfirstlane_b32 s6, v3
	v_sub_u32_e32 v3, 0, v2
	v_rcp_iflag_f32_e32 v4, v4
	v_add_u32_e32 v5, s6, v1
	v_mul_f32_e32 v4, 0x4f7ffffe, v4
	v_cvt_u32_f32_e32 v4, v4
	v_mul_lo_u32 v1, v3, v4
	v_mul_hi_u32 v1, v4, v1
	v_add_u32_e32 v1, v4, v1
	v_mul_hi_u32 v1, v5, v1
	v_mul_lo_u32 v3, v1, v2
	v_sub_u32_e32 v3, v5, v3
	v_add_u32_e32 v4, 1, v1
	v_cmp_ge_u32_e32 vcc, v3, v2
	s_nop 1
	v_cndmask_b32_e32 v1, v1, v4, vcc
	v_sub_u32_e32 v4, v3, v2
	v_cndmask_b32_e32 v3, v3, v4, vcc
	v_add_u32_e32 v4, 1, v1
	v_cmp_ge_u32_e32 vcc, v3, v2
	v_add_u32_e32 v3, 1, v5
	s_nop 0
	v_cndmask_b32_e32 v1, v1, v4, vcc
	v_mul_lo_u32 v4, v2, v1
	v_add_u32_e32 v2, v4, v2
	v_cmp_ne_u32_e32 vcc, v3, v2
	s_and_saveexec_b64 s[6:7], vcc
	s_xor_b64 s[6:7], exec, s[6:7]
	s_cbranch_execz .LBB0_102
	s_waitcnt lgkmcnt(0)
	s_add_u32 s12, s96, 0x183400
	s_addc_u32 s13, s97, 0
	v_add_u32_e32 v3, 1, v1
	v_mul_lo_u32 v3, v3, v0
	v_mov_b32_e32 v0, 0
	buffer_inv sc1
	global_load_dword v0, v0, s[12:13] sc1
	s_waitcnt vmcnt(0)
	v_cmp_lt_u32_e32 vcc, v0, v3
	s_and_saveexec_b64 s[8:9], vcc
	s_cbranch_execz .LBB0_101
	s_add_u32 s10, s96, 0x180200
	s_addc_u32 s11, s97, 0
	s_mov_b32 s24, 1
	s_mov_b64 s[14:15], 0
	v_mov_b32_e32 v0, 0
	s_branch .LBB0_92

; __device__ __forceinline__ unsigned xb_ld(unsigned* p)              { return __hip_atomic_load(p, __ATOMIC_RELAXED, __HIP_MEMORY_SCOPE_AGENT); }
; #define XB_SPIN(cond, bar) do { unsigned _sp = 0; while (cond) { __builtin_amdgcn_s_sleep(1); \
;     if ((++_sp & 255u) == 0u) { if (xb_ld(&(bar)[XB_TMO])) break; if (_sp > XB_SPIN_CAP) { atomicAdd(&(bar)[XB_TMO], 1u); break; } } } } while (0)
; __device__ __forceinline__ void xcd_barrier(const XcdBarrier& b) {
;     ...
;             XB_SPIN(xb_ld(&bar[XB_XGEN(b.x)]) == gen, bar);
.LBB0_96:
	global_load_dword v2, v0, s[12:13] sc1
	s_add_i32 s24, s24, 1
	s_mov_b64 s[20:21], -1
	s_waitcnt vmcnt(0)
	v_cmp_ge_u32_e32 vcc, v2, v3
	s_orn2_b64 s[18:19], vcc, exec
	s_branch .LBB0_91

; __device__ __forceinline__ unsigned xb_ld(unsigned* p)              { return __hip_atomic_load(p, __ATOMIC_RELAXED, __HIP_MEMORY_SCOPE_AGENT); }
; __device__ __forceinline__ unsigned xb_add(unsigned* p, unsigned v) { return __hip_atomic_fetch_add(p, v, __ATOMIC_RELAXED, __HIP_MEMORY_SCOPE_AGENT); }
; #define XB_SPIN(cond, bar) do { unsigned _sp = 0; while (cond) { __builtin_amdgcn_s_sleep(1); \
;     if ((++_sp & 255u) == 0u) { if (xb_ld(&(bar)[XB_TMO])) break; if (_sp > XB_SPIN_CAP) { atomicAdd(&(bar)[XB_TMO], 1u); break; } } } } while (0)
; __device__ __forceinline__ void xcd_barrier(const XcdBarrier& b) {
;     ...
;             const unsigned og = xb_add(&bar[XB_TOP], 1u);
;             const unsigned tg = og / nx;
;             if (og + 1u == (tg + 1u) * nx) xb_add(&bar[XB_TOPGEN], 1u);
;             else XB_SPIN(xb_ld(&bar[XB_TOPGEN]) == tg, bar);
.LBB0_105:
	s_or_b64 exec, exec, s[8:9]
	v_cvt_f32_u32_e32 v3, v0
	s_waitcnt vmcnt(0)
	v_readfirstlane_b32 s6, v2
	s_add_u32 s8, s96, 0x183500
	s_addc_u32 s9, s97, 0
	v_rcp_iflag_f32_e32 v3, v3
	v_add_u32_e32 v1, s6, v1
	v_add_u32_e32 v4, 1, v1
	s_mov_b64 s[10:11], -1
	v_mul_f32_e32 v2, 0x4f7ffffe, v3
	v_cvt_u32_f32_e32 v2, v2
	v_sub_u32_e32 v3, 0, v0
	v_mul_lo_u32 v3, v3, v2
	v_mul_hi_u32 v3, v2, v3
	v_add_u32_e32 v2, v2, v3
	v_mul_hi_u32 v2, v1, v2
	v_mul_lo_u32 v3, v2, v0
	v_sub_u32_e32 v1, v1, v3
	v_add_u32_e32 v5, 1, v2
	v_cmp_ge_u32_e32 vcc, v1, v0
	v_sub_u32_e32 v3, v1, v0
	s_nop 0
	v_cndmask_b32_e32 v2, v2, v5, vcc
	v_cndmask_b32_e32 v1, v1, v3, vcc
	v_add_u32_e32 v3, 1, v2
	v_cmp_ge_u32_e32 vcc, v1, v0
	s_nop 1
	v_cndmask_b32_e32 v2, v2, v3, vcc
	v_mul_lo_u32 v1, v0, v2
	v_add_u32_e32 v0, v1, v0
	v_mov_b32_e32 v5, v0
	v_cmp_ne_u32_e32 vcc, v4, v0
	v_mov_b64_e32 v[0:1], s[8:9]
	s_and_saveexec_b64 s[6:7], vcc
	s_cbranch_execz .LBB0_117
	v_mov_b32_e32 v0, 0
	global_load_dword v1, v0, s[8:9] offset:-256 sc1
	s_mov_b64 s[14:15], 0
	s_waitcnt vmcnt(0)
	v_cmp_lt_u32_e32 vcc, v1, v5
	s_and_saveexec_b64 s[12:13], vcc
	s_cbranch_execz .LBB0_116
	s_add_u32 s10, s96, 0x180200
	s_addc_u32 s11, s97, 0
	s_mov_b32 s24, 1
	s_branch .LBB0_109

; __device__ __forceinline__ unsigned xb_ld(unsigned* p)              { return __hip_atomic_load(p, __ATOMIC_RELAXED, __HIP_MEMORY_SCOPE_AGENT); }
; #define XB_SPIN(cond, bar) do { unsigned _sp = 0; while (cond) { __builtin_amdgcn_s_sleep(1); \
;     if ((++_sp & 255u) == 0u) { if (xb_ld(&(bar)[XB_TMO])) break; if (_sp > XB_SPIN_CAP) { atomicAdd(&(bar)[XB_TMO], 1u); break; } } } } while (0)
; __device__ __forceinline__ void xcd_barrier(const XcdBarrier& b) {
;     ...
;             else XB_SPIN(xb_ld(&bar[XB_TOPGEN]) == tg, bar);
.LBB0_113:
	global_load_dword v1, v0, s[8:9] offset:-256 sc1
	s_add_i32 s24, s24, 1
	s_mov_b64 s[18:19], -1
	s_waitcnt vmcnt(0)
	v_cmp_ge_u32_e32 vcc, v1, v5
	s_orn2_b64 s[22:23], vcc, exec
	s_branch .LBB0_108

; __device__ __forceinline__ unsigned xb_ld(unsigned* p)              { return __hip_atomic_load(p, __ATOMIC_RELAXED, __HIP_MEMORY_SCOPE_AGENT); }
; __device__ __forceinline__ unsigned xb_add(unsigned* p, unsigned v) { return __hip_atomic_fetch_add(p, v, __ATOMIC_RELAXED, __HIP_MEMORY_SCOPE_AGENT); }
; #define XB_SPIN(cond, bar) do { unsigned _sp = 0; while (cond) { __builtin_amdgcn_s_sleep(1); \
;     if ((++_sp & 255u) == 0u) { if (xb_ld(&(bar)[XB_TMO])) break; if (_sp > XB_SPIN_CAP) { atomicAdd(&(bar)[XB_TMO], 1u); break; } } } } while (0)
; __device__ __forceinline__ void xcd_barrier(const XcdBarrier& b) {
;     ...
;         const unsigned old = xb_add(&bar[XB_XSUB(b.x)], 1u);
;         const unsigned gen = old / nloc;
;         if (old + 1u == (gen + 1u) * nloc) {
;             __builtin_amdgcn_fence(__ATOMIC_RELEASE, "agent");
;             asm volatile("s_waitcnt vmcnt(0)" ::: "memory");
;             const unsigned og = xb_add(&bar[XB_TOP], 1u);
;             const unsigned tg = og / nx;
;             if (og + 1u == (tg + 1u) * nx) xb_add(&bar[XB_TOPGEN], 1u);
;             else XB_SPIN(xb_ld(&bar[XB_TOPGEN]) == tg, bar);
;             __builtin_amdgcn_fence(__ATOMIC_ACQUIRE, "agent");
;             xb_add(&bar[XB_XGEN(b.x)], 1u);
;             asm volatile("s_waitcnt vmcnt(0)" ::: "memory");
;         } else {
;             XB_SPIN(xb_ld(&bar[XB_XGEN(b.x)]) == gen, bar);
;             __builtin_amdgcn_fence(__ATOMIC_ACQUIRE, "agent");
;             asm volatile("s_waitcnt vmcnt(0)" ::: "memory");
.LBB0_191:
	s_or_b64 exec, exec, s[6:7]
	v_cvt_f32_u32_e32 v4, v2
	s_waitcnt vmcnt(0)
	v_readfirstlane_b32 s4, v3
	v_sub_u32_e32 v3, 0, v2
	v_rcp_iflag_f32_e32 v4, v4
	v_add_u32_e32 v5, s4, v1
	v_mul_f32_e32 v4, 0x4f7ffffe, v4
	v_cvt_u32_f32_e32 v4, v4
	v_mul_lo_u32 v1, v3, v4
	v_mul_hi_u32 v1, v4, v1
	v_add_u32_e32 v1, v4, v1
	v_mul_hi_u32 v1, v5, v1
	v_mul_lo_u32 v3, v1, v2
	v_sub_u32_e32 v3, v5, v3
	v_add_u32_e32 v4, 1, v1
	v_cmp_ge_u32_e32 vcc, v3, v2
	s_nop 1
	v_cndmask_b32_e32 v1, v1, v4, vcc
	v_sub_u32_e32 v4, v3, v2
	v_cndmask_b32_e32 v3, v3, v4, vcc
	v_add_u32_e32 v4, 1, v1
	v_cmp_ge_u32_e32 vcc, v3, v2
	v_add_u32_e32 v3, 1, v5
	s_nop 0
	v_cndmask_b32_e32 v1, v1, v4, vcc
	v_mul_lo_u32 v4, v2, v1
	v_add_u32_e32 v2, v4, v2
	v_cmp_ne_u32_e32 vcc, v3, v2
	s_and_saveexec_b64 s[4:5], vcc
	s_xor_b64 s[4:5], exec, s[4:5]
	s_cbranch_execz .LBB0_205
	s_waitcnt lgkmcnt(0)
	s_add_u32 s10, s96, 0x183400
	s_addc_u32 s11, s97, 0
	v_add_u32_e32 v3, 1, v1
	v_mul_lo_u32 v3, v3, v0
	v_mov_b32_e32 v0, 0
	buffer_inv sc1
	global_load_dword v0, v0, s[10:11] sc1
	s_waitcnt vmcnt(0)
	v_cmp_lt_u32_e32 vcc, v0, v3
	s_and_saveexec_b64 s[6:7], vcc
	s_cbranch_execz .LBB0_204
	s_add_u32 s8, s96, 0x180200
	s_addc_u32 s9, s97, 0
	s_mov_b32 s22, 1
	s_mov_b64 s[12:13], 0
	v_mov_b32_e32 v0, 0
	s_branch .LBB0_195

; __device__ __forceinline__ unsigned xb_ld(unsigned* p)              { return __hip_atomic_load(p, __ATOMIC_RELAXED, __HIP_MEMORY_SCOPE_AGENT); }
; #define XB_SPIN(cond, bar) do { unsigned _sp = 0; while (cond) { __builtin_amdgcn_s_sleep(1); \
;     if ((++_sp & 255u) == 0u) { if (xb_ld(&(bar)[XB_TMO])) break; if (_sp > XB_SPIN_CAP) { atomicAdd(&(bar)[XB_TMO], 1u); break; } } } } while (0)
; __device__ __forceinline__ void xcd_barrier(const XcdBarrier& b) {
;     ...
;             XB_SPIN(xb_ld(&bar[XB_XGEN(b.x)]) == gen, bar);
.LBB0_199:
	global_load_dword v2, v0, s[10:11] sc1
	s_add_i32 s22, s22, 1
	s_mov_b64 s[18:19], -1
	s_waitcnt vmcnt(0)
	v_cmp_ge_u32_e32 vcc, v2, v3
	s_orn2_b64 s[16:17], vcc, exec
	s_branch .LBB0_194

; __device__ __forceinline__ unsigned xb_ld(unsigned* p)              { return __hip_atomic_load(p, __ATOMIC_RELAXED, __HIP_MEMORY_SCOPE_AGENT); }
; __device__ __forceinline__ unsigned xb_add(unsigned* p, unsigned v) { return __hip_atomic_fetch_add(p, v, __ATOMIC_RELAXED, __HIP_MEMORY_SCOPE_AGENT); }
; #define XB_SPIN(cond, bar) do { unsigned _sp = 0; while (cond) { __builtin_amdgcn_s_sleep(1); \
;     if ((++_sp & 255u) == 0u) { if (xb_ld(&(bar)[XB_TMO])) break; if (_sp > XB_SPIN_CAP) { atomicAdd(&(bar)[XB_TMO], 1u); break; } } } } while (0)
; __device__ __forceinline__ void xcd_barrier(const XcdBarrier& b) {
;     ...
;             const unsigned og = xb_add(&bar[XB_TOP], 1u);
;             const unsigned tg = og / nx;
;             if (og + 1u == (tg + 1u) * nx) xb_add(&bar[XB_TOPGEN], 1u);
;             else XB_SPIN(xb_ld(&bar[XB_TOPGEN]) == tg, bar);
.LBB0_208:
	s_or_b64 exec, exec, s[6:7]
	v_cvt_f32_u32_e32 v3, v0
	s_waitcnt vmcnt(0)
	v_readfirstlane_b32 s4, v2
	s_add_u32 s6, s96, 0x183500
	s_addc_u32 s7, s97, 0
	v_rcp_iflag_f32_e32 v3, v3
	v_add_u32_e32 v1, s4, v1
	v_add_u32_e32 v4, 1, v1
	s_mov_b64 s[8:9], -1
	v_mul_f32_e32 v2, 0x4f7ffffe, v3
	v_cvt_u32_f32_e32 v2, v2
	v_sub_u32_e32 v3, 0, v0
	v_mul_lo_u32 v3, v3, v2
	v_mul_hi_u32 v3, v2, v3
	v_add_u32_e32 v2, v2, v3
	v_mul_hi_u32 v2, v1, v2
	v_mul_lo_u32 v3, v2, v0
	v_sub_u32_e32 v1, v1, v3
	v_add_u32_e32 v5, 1, v2
	v_cmp_ge_u32_e32 vcc, v1, v0
	v_sub_u32_e32 v3, v1, v0
	s_nop 0
	v_cndmask_b32_e32 v2, v2, v5, vcc
	v_cndmask_b32_e32 v1, v1, v3, vcc
	v_add_u32_e32 v3, 1, v2
	v_cmp_ge_u32_e32 vcc, v1, v0
	s_nop 1
	v_cndmask_b32_e32 v2, v2, v3, vcc
	v_mul_lo_u32 v1, v0, v2
	v_add_u32_e32 v0, v1, v0
	v_mov_b32_e32 v5, v0
	v_cmp_ne_u32_e32 vcc, v4, v0
	v_mov_b64_e32 v[0:1], s[6:7]
	s_and_saveexec_b64 s[4:5], vcc
	s_cbranch_execz .LBB0_220
	v_mov_b32_e32 v0, 0
	global_load_dword v1, v0, s[6:7] offset:-256 sc1
	s_mov_b64 s[12:13], 0
	s_waitcnt vmcnt(0)
	v_cmp_lt_u32_e32 vcc, v1, v5
	s_and_saveexec_b64 s[10:11], vcc
	s_cbranch_execz .LBB0_219
	s_add_u32 s8, s96, 0x180200
	s_addc_u32 s9, s97, 0
	s_mov_b32 s22, 1
	s_branch .LBB0_212

; __device__ __forceinline__ unsigned xb_ld(unsigned* p)              { return __hip_atomic_load(p, __ATOMIC_RELAXED, __HIP_MEMORY_SCOPE_AGENT); }
; #define XB_SPIN(cond, bar) do { unsigned _sp = 0; while (cond) { __builtin_amdgcn_s_sleep(1); \
;     if ((++_sp & 255u) == 0u) { if (xb_ld(&(bar)[XB_TMO])) break; if (_sp > XB_SPIN_CAP) { atomicAdd(&(bar)[XB_TMO], 1u); break; } } } } while (0)
; __device__ __forceinline__ void xcd_barrier(const XcdBarrier& b) {
;     ...
;             else XB_SPIN(xb_ld(&bar[XB_TOPGEN]) == tg, bar);
.LBB0_216:
	global_load_dword v1, v0, s[6:7] offset:-256 sc1
	s_add_i32 s22, s22, 1
	s_mov_b64 s[16:17], -1
	s_waitcnt vmcnt(0)
	v_cmp_ge_u32_e32 vcc, v1, v5
	s_orn2_b64 s[20:21], vcc, exec
	s_branch .LBB0_211

; __device__ __forceinline__ unsigned xb_ld(unsigned* p)              { return __hip_atomic_load(p, __ATOMIC_RELAXED, __HIP_MEMORY_SCOPE_AGENT); }
; __device__ __forceinline__ unsigned xb_add(unsigned* p, unsigned v) { return __hip_atomic_fetch_add(p, v, __ATOMIC_RELAXED, __HIP_MEMORY_SCOPE_AGENT); }
; #define XB_SPIN(cond, bar) do { unsigned _sp = 0; while (cond) { __builtin_amdgcn_s_sleep(1); \
;     if ((++_sp & 255u) == 0u) { if (xb_ld(&(bar)[XB_TMO])) break; if (_sp > XB_SPIN_CAP) { atomicAdd(&(bar)[XB_TMO], 1u); break; } } } } while (0)
; __device__ __forceinline__ void xcd_barrier(const XcdBarrier& b) {
;     ...
;         const unsigned old = xb_add(&bar[XB_XSUB(b.x)], 1u);
;         const unsigned gen = old / nloc;
;         if (old + 1u == (gen + 1u) * nloc) {
;             __builtin_amdgcn_fence(__ATOMIC_RELEASE, "agent");
;             asm volatile("s_waitcnt vmcnt(0)" ::: "memory");
;             const unsigned og = xb_add(&bar[XB_TOP], 1u);
;             const unsigned tg = og / nx;
;             if (og + 1u == (tg + 1u) * nx) xb_add(&bar[XB_TOPGEN], 1u);
;             else XB_SPIN(xb_ld(&bar[XB_TOPGEN]) == tg, bar);
;             __builtin_amdgcn_fence(__ATOMIC_ACQUIRE, "agent");
;             xb_add(&bar[XB_XGEN(b.x)], 1u);
;             asm volatile("s_waitcnt vmcnt(0)" ::: "memory");
;         } else {
;             XB_SPIN(xb_ld(&bar[XB_XGEN(b.x)]) == gen, bar);
;             __builtin_amdgcn_fence(__ATOMIC_ACQUIRE, "agent");
;             asm volatile("s_waitcnt vmcnt(0)" ::: "memory");
.LBB0_458:
	s_or_b64 exec, exec, s[6:7]
	v_cvt_f32_u32_e32 v4, v2
	s_waitcnt vmcnt(0)
	v_readfirstlane_b32 s4, v3
	v_sub_u32_e32 v3, 0, v2
	v_rcp_iflag_f32_e32 v4, v4
	v_add_u32_e32 v5, s4, v1
	v_mul_f32_e32 v4, 0x4f7ffffe, v4
	v_cvt_u32_f32_e32 v4, v4
	v_mul_lo_u32 v1, v3, v4
	v_mul_hi_u32 v1, v4, v1
	v_add_u32_e32 v1, v4, v1
	v_mul_hi_u32 v1, v5, v1
	v_mul_lo_u32 v3, v1, v2
	v_sub_u32_e32 v3, v5, v3
	v_add_u32_e32 v4, 1, v1
	v_cmp_ge_u32_e32 vcc, v3, v2
	s_nop 1
	v_cndmask_b32_e32 v1, v1, v4, vcc
	v_sub_u32_e32 v4, v3, v2
	v_cndmask_b32_e32 v3, v3, v4, vcc
	v_add_u32_e32 v4, 1, v1
	v_cmp_ge_u32_e32 vcc, v3, v2
	v_add_u32_e32 v3, 1, v5
	s_nop 0
	v_cndmask_b32_e32 v1, v1, v4, vcc
	v_mul_lo_u32 v4, v2, v1
	v_add_u32_e32 v2, v4, v2
	v_cmp_ne_u32_e32 vcc, v3, v2
	s_and_saveexec_b64 s[4:5], vcc
	s_xor_b64 s[4:5], exec, s[4:5]
	s_cbranch_execz .LBB0_472
	s_waitcnt lgkmcnt(0)
	s_add_u32 s12, s96, 0x183400
	s_addc_u32 s13, s97, 0
	v_add_u32_e32 v3, 1, v1
	v_mul_lo_u32 v3, v3, v0
	v_mov_b32_e32 v0, 0
	buffer_inv sc1
	global_load_dword v0, v0, s[12:13] sc1
	s_waitcnt vmcnt(0)
	v_cmp_lt_u32_e32 vcc, v0, v3
	s_and_saveexec_b64 s[6:7], vcc
	s_cbranch_execz .LBB0_471
	s_add_u32 s8, s96, 0x180200
	s_addc_u32 s9, s97, 0
	s_mov_b32 s24, 1
	s_mov_b64 s[14:15], 0
	v_mov_b32_e32 v0, 0
	s_branch .LBB0_462

; __device__ __forceinline__ unsigned xb_ld(unsigned* p)              { return __hip_atomic_load(p, __ATOMIC_RELAXED, __HIP_MEMORY_SCOPE_AGENT); }
; __device__ __forceinline__ unsigned xb_add(unsigned* p, unsigned v) { return __hip_atomic_fetch_add(p, v, __ATOMIC_RELAXED, __HIP_MEMORY_SCOPE_AGENT); }
; #define XB_SPIN(cond, bar) do { unsigned _sp = 0; while (cond) { __builtin_amdgcn_s_sleep(1); \
;     if ((++_sp & 255u) == 0u) { if (xb_ld(&(bar)[XB_TMO])) break; if (_sp > XB_SPIN_CAP) { atomicAdd(&(bar)[XB_TMO], 1u); break; } } } } while (0)
; __device__ __forceinline__ void xcd_barrier(const XcdBarrier& b) {
;     ...
;             const unsigned og = xb_add(&bar[XB_TOP], 1u);
;             const unsigned tg = og / nx;
;             if (og + 1u == (tg + 1u) * nx) xb_add(&bar[XB_TOPGEN], 1u);
;             else XB_SPIN(xb_ld(&bar[XB_TOPGEN]) == tg, bar);
.LBB0_475:
	s_or_b64 exec, exec, s[6:7]
	v_cvt_f32_u32_e32 v3, v0
	s_waitcnt vmcnt(0)
	v_readfirstlane_b32 s4, v2
	s_add_u32 s6, s96, 0x183500
	s_addc_u32 s7, s97, 0
	v_rcp_iflag_f32_e32 v3, v3
	v_add_u32_e32 v1, s4, v1
	v_add_u32_e32 v4, 1, v1
	s_mov_b64 s[8:9], -1
	v_mul_f32_e32 v2, 0x4f7ffffe, v3
	v_cvt_u32_f32_e32 v2, v2
	v_sub_u32_e32 v3, 0, v0
	v_mul_lo_u32 v3, v3, v2
	v_mul_hi_u32 v3, v2, v3
	v_add_u32_e32 v2, v2, v3
	v_mul_hi_u32 v2, v1, v2
	v_mul_lo_u32 v3, v2, v0
	v_sub_u32_e32 v1, v1, v3
	v_add_u32_e32 v5, 1, v2
	v_cmp_ge_u32_e32 vcc, v1, v0
	v_sub_u32_e32 v3, v1, v0
	s_nop 0
	v_cndmask_b32_e32 v2, v2, v5, vcc
	v_cndmask_b32_e32 v1, v1, v3, vcc
	v_add_u32_e32 v3, 1, v2
	v_cmp_ge_u32_e32 vcc, v1, v0
	s_nop 1
	v_cndmask_b32_e32 v2, v2, v3, vcc
	v_mul_lo_u32 v1, v0, v2
	v_add_u32_e32 v0, v1, v0
	v_mov_b32_e32 v5, v0
	v_cmp_ne_u32_e32 vcc, v4, v0
	v_mov_b64_e32 v[0:1], s[6:7]
	s_and_saveexec_b64 s[4:5], vcc
	s_cbranch_execz .LBB0_487
	v_mov_b32_e32 v0, 0
	global_load_dword v1, v0, s[6:7] offset:-256 sc1
	s_mov_b64 s[14:15], 0
	s_waitcnt vmcnt(0)
	v_cmp_lt_u32_e32 vcc, v1, v5
	s_and_saveexec_b64 s[12:13], vcc
	s_cbranch_execz .LBB0_486
	s_add_u32 s8, s96, 0x180200
	s_addc_u32 s9, s97, 0
	s_mov_b32 s24, 1
	s_branch .LBB0_479

; __device__ __forceinline__ unsigned xb_ld(unsigned* p)              { return __hip_atomic_load(p, __ATOMIC_RELAXED, __HIP_MEMORY_SCOPE_AGENT); }
; #define XB_SPIN(cond, bar) do { unsigned _sp = 0; while (cond) { __builtin_amdgcn_s_sleep(1); \
;     if ((++_sp & 255u) == 0u) { if (xb_ld(&(bar)[XB_TMO])) break; if (_sp > XB_SPIN_CAP) { atomicAdd(&(bar)[XB_TMO], 1u); break; } } } } while (0)
; __device__ __forceinline__ void xcd_barrier(const XcdBarrier& b) {
;     ...
;             else XB_SPIN(xb_ld(&bar[XB_TOPGEN]) == tg, bar);
.LBB0_483:
	global_load_dword v1, v0, s[6:7] offset:-256 sc1
	s_add_i32 s24, s24, 1
	s_mov_b64 s[18:19], -1
	s_waitcnt vmcnt(0)
	v_cmp_ge_u32_e32 vcc, v1, v5
	s_orn2_b64 s[22:23], vcc, exec
	s_branch .LBB0_478
